# Wo and down-proj epilogues: all 16 residual loads of a tile issued before the first wait (hipcc waited vmcnt(0) after the first 4, exposing a second memory round trip per tile); wait is now vmcnt(12)
# speedup vs baseline: 1.0087x; 1.0060x over previous
; __device__ __forceinline__ unsigned cvt_pk_bf16(float lo, float hi) { f32x2c v = {lo, hi}; bf16x2c b = __builtin_convertvector(v, bf16x2c); return __builtin_bit_cast(unsigned, b); }
;     __device__ __forceinline__ void operator()(const f32x4 (&acc)[2][2][4][2], const Unit& u, int wr, int wc, int fr_, int fq_) const {
;     ...
;         const int col0 = u.pn * BM + wc * 32 + 8 * fq;
;         const size_t off0 = (size_t)(u.pm * BM + wr * 64 + fr) * 2048 + col0;
;         u32x4 bw[2][4][2];
; #pragma unroll
;         for (int ai = 0; ai < 2; ++ai)
; #pragma unroll
;             for (int m = 0; m < 4; ++m)
; #pragma unroll
;                 for (int bj = 0; bj < 2; ++bj) bw[ai][m][bj] = *(const u32x4*)(xb + off0 + (size_t)(ai * HALF + m * 16) * 2048 + bj * HALF);
;         f32x4 cv[2][2];
; #pragma unroll
;         for (int bj = 0; bj < 2; ++bj)
; #pragma unroll
;             for (int n = 0; n < 2; ++n) cv[bj][n] = cs ? *(const f32x4*)(cs + col0 + bj * HALF + n * 4) : (f32x4){1.f, 1.f, 1.f, 1.f};
; #pragma unroll
;         for (int ai = 0; ai < 2; ++ai)
; #pragma unroll
;             for (int m = 0; m < 4; ++m) { const int row = u.pm * BM + ai * HALF + wr * 64 + m * 16 + fr; const size_t off = off0 + (size_t)(ai * HALF + m * 16) * 2048; float s = 0.f;
; #pragma unroll
;                 for (int bj = 0; bj < 2; ++bj) { const u32x4 w0 = bw[ai][m][bj];
;                     const f32x4 v0 = (f32x4){bf_lo(w0.x), bf_hi(w0.x), bf_lo(w0.y), bf_hi(w0.y)} + acc[ai][bj][m][0] * cv[bj][0];
;                     const f32x4 v1 = (f32x4){bf_lo(w0.z), bf_hi(w0.z), bf_lo(w0.w), bf_hi(w0.w)} + acc[ai][bj][m][1] * cv[bj][1];
;                     if (out) { *(f32x4*)(out + off + bj * HALF) = v0; *(f32x4*)(out + off + bj * HALF + 4) = v1; }
;                     u32x4 w; w.x = cvt_pk_bf16(v0[0], v0[1]); w.y = cvt_pk_bf16(v0[2], v0[3]); w.z = cvt_pk_bf16(v1[0], v1[1]); w.w = cvt_pk_bf16(v1[2], v1[3]); if (!out) *(u32x4*)(xb + off + bj * HALF) = w;
;                     s += ((v0[0] * v0[0] + v0[1] * v0[1]) + (v0[2] * v0[2] + v0[3] * v0[3])) + ((v1[0] * v1[0] + v1[1] * v1[1]) + (v1[2] * v1[2] + v1[3] * v1[3])); }
;                 if (!out) { s = sum_fq(s); if (fq == 0) ssn[(size_t)row * 32 + u.pn * 4 + wc] = s; } }
.LBB0_605:
	s_lshl_b32 s2, s50, 8
	v_mov_b32_e32 v209, v1
	v_mov_b32_e32 v119, v206
	s_or_b32 s2, s2, s45
	s_lshl_b32 s4, s50, 2
	v_lshl_add_u32 v118, v209, 3, s2
	s_lshl_b32 s2, s80, 8
	s_add_i32 s2, s2, s44
	v_add_u32_e32 v202, s2, v119
	v_ashrrev_i32_e32 v203, 31, v202
	v_lshlrev_b64 v[120:121], 11, v[202:203]
	v_ashrrev_i32_e32 v119, 31, v118
	v_lshl_add_u64 v[118:119], v[120:121], 0, v[118:119]
	v_lshl_add_u64 v[204:205], v[118:119], 1, s[10:11]
	global_load_dwordx4 v[210:213], v[204:205], off
	global_load_dwordx4 v[186:189], v[204:205], off offset:256
	v_add_co_u32_e32 v118, vcc, s24, v204
	s_ashr_i32 s5, s4, 31
	s_nop 0
	v_addc_co_u32_e32 v119, vcc, 0, v205, vcc
	global_load_dwordx4 v[182:185], v[118:119], off
	global_load_dwordx4 v[178:181], v[118:119], off offset:256
	v_add_co_u32_e32 v118, vcc, s19, v204
	s_nop 0
	s_nop 0
	v_addc_co_u32_e32 v119, vcc, 0, v205, vcc
	global_load_dwordx4 v[174:177], v[118:119], off
	global_load_dwordx4 v[170:173], v[118:119], off offset:256
	v_add_co_u32_e32 v118, vcc, s25, v204
	s_nop 0
	s_nop 0
	v_addc_co_u32_e32 v119, vcc, 0, v205, vcc
	global_load_dwordx4 v[166:169], v[118:119], off
	global_load_dwordx4 v[162:165], v[118:119], off offset:256
	v_add_co_u32_e32 v118, vcc, s1, v204
	s_nop 0
	s_nop 0
	v_addc_co_u32_e32 v119, vcc, 0, v205, vcc
	global_load_dwordx4 v[158:161], v[118:119], off
	global_load_dwordx4 v[154:157], v[118:119], off offset:256
	v_add_co_u32_e32 v118, vcc, s0, v204
	s_nop 0
	s_nop 0
	v_addc_co_u32_e32 v119, vcc, 0, v205, vcc
	global_load_dwordx4 v[142:145], v[118:119], off
	global_load_dwordx4 v[138:141], v[118:119], off offset:256
	v_add_co_u32_e32 v118, vcc, s64, v204
	s_nop 0
	s_nop 0
	v_addc_co_u32_e32 v119, vcc, 0, v205, vcc
	global_load_dwordx4 v[134:137], v[118:119], off
	global_load_dwordx4 v[130:133], v[118:119], off offset:256
	v_add_co_u32_e32 v118, vcc, s65, v204
	s_nop 0
	s_nop 0
	v_addc_co_u32_e32 v119, vcc, 0, v205, vcc
	global_load_dwordx4 v[126:129], v[118:119], off
	s_nop 0
	global_load_dwordx4 v[118:121], v[118:119], off offset:256
	s_waitcnt vmcnt(12)
	v_lshlrev_b32_e32 v214, 16, v210
	v_and_b32_e32 v215, 0xffff0000, v210
	v_lshlrev_b32_e32 v210, 16, v211
	v_and_b32_e32 v211, 0xffff0000, v211
	v_pk_add_f32 v[152:153], v[152:153], v[210:211]
	v_lshlrev_b32_e32 v210, 16, v212
	v_and_b32_e32 v211, 0xffff0000, v212
	v_lshlrev_b32_e32 v212, 16, v213
	v_and_b32_e32 v213, 0xffff0000, v213
	v_pk_add_f32 v[150:151], v[150:151], v[214:215]
	v_pk_add_f32 v[212:213], v[148:149], v[212:213]
	v_pk_add_f32 v[210:211], v[146:147], v[210:211]
	v_cvt_pk_bf16_f32 v146, v150, v151
	v_cvt_pk_bf16_f32 v147, v152, v153
	v_cvt_pk_bf16_f32 v148, v210, v211
	v_cvt_pk_bf16_f32 v149, v212, v213
	global_store_dwordx4 v[204:205], v[146:149], off
	v_cmp_eq_u32_e32 vcc, 0, v209
	s_nop 0
	v_mul_f32_e32 v146, v151, v151
	v_mul_f32_e32 v147, v153, v153
	v_fmac_f32_e32 v146, v150, v150
	v_fmac_f32_e32 v147, v152, v152
	v_add_f32_e32 v146, v146, v147
	v_mul_f32_e32 v147, v211, v211
	v_mul_f32_e32 v148, v213, v213
	v_fmac_f32_e32 v147, v210, v210
	v_fmac_f32_e32 v148, v212, v212
	v_add_f32_e32 v147, v147, v148
	v_add_f32_e32 v150, v146, v147
	v_lshlrev_b32_e32 v146, 16, v186
	v_and_b32_e32 v147, 0xffff0000, v186
	v_lshlrev_b32_e32 v148, 16, v187
	v_and_b32_e32 v149, 0xffff0000, v187
	v_pk_add_f32 v[124:125], v[124:125], v[148:149]
	v_pk_add_f32 v[122:123], v[122:123], v[146:147]
	v_lshlrev_b32_e32 v146, 16, v188
	v_and_b32_e32 v147, 0xffff0000, v188
	v_lshlrev_b32_e32 v148, 16, v189
	v_and_b32_e32 v149, 0xffff0000, v189
	v_pk_add_f32 v[148:149], v[116:117], v[148:149]
	v_pk_add_f32 v[146:147], v[114:115], v[146:147]
	v_cvt_pk_bf16_f32 v114, v122, v123
	v_cvt_pk_bf16_f32 v115, v124, v125
	v_cvt_pk_bf16_f32 v116, v146, v147
	v_cvt_pk_bf16_f32 v117, v148, v149
	global_store_dwordx4 v[204:205], v[114:117], off offset:256
	s_nop 1
	v_mul_f32_e32 v114, v123, v123
	v_mul_f32_e32 v115, v125, v125
	v_fmac_f32_e32 v114, v122, v122
	v_fmac_f32_e32 v115, v124, v124
	v_add_f32_e32 v114, v114, v115
	v_mul_f32_e32 v115, v147, v147
	v_mul_f32_e32 v116, v149, v149
	v_fmac_f32_e32 v115, v146, v146
	v_fmac_f32_e32 v116, v148, v148
	v_add_f32_e32 v115, v115, v116
	v_add_f32_e32 v114, v114, v115
	v_add_f32_e32 v114, v150, v114
	v_mov_b32_e32 v115, v114
	s_nop 1
	v_permlane16_swap_b32 v115, v114
	s_nop 0
	v_add_f32_e32 v114, v115, v114
	v_mov_b32_e32 v115, v114
	s_nop 1
	v_permlane32_swap_b32 v115, v114
	s_and_saveexec_b64 s[2:3], vcc
	s_cbranch_execz .LBB0_607
	v_lshlrev_b64 v[116:117], 7, v[202:203]
	v_lshl_add_u64 v[116:117], s[12:13], 0, v[116:117]
	v_lshl_add_u64 v[116:117], s[4:5], 2, v[116:117]
	s_lshl_b32 s50, s43, 2
	v_lshl_add_u64 v[116:117], v[116:117], 0, s[50:51]
	v_add_f32_e32 v114, v115, v114
	global_store_dword v[116:117], v114, off

;     __device__ __forceinline__ void operator()(const f32x4 (&acc)[2][2][4][2], const Unit& u, int wr, int wc, int fr_, int fq_) const {
;     ...
;         const int col0 = u.pn * BM + wc * 32 + 8 * fq;
;         const size_t off0 = (size_t)(u.pm * BM + wr * 64 + fr) * 2048 + col0;
;         u32x4 bw[2][4][2];
; #pragma unroll
;         for (int ai = 0; ai < 2; ++ai)
; #pragma unroll
;             for (int m = 0; m < 4; ++m)
; #pragma unroll
;                 for (int bj = 0; bj < 2; ++bj) bw[ai][m][bj] = *(const u32x4*)(xb + off0 + (size_t)(ai * HALF + m * 16) * 2048 + bj * HALF);
;         f32x4 cv[2][2];
; #pragma unroll
;         for (int bj = 0; bj < 2; ++bj)
; #pragma unroll
;             for (int n = 0; n < 2; ++n) cv[bj][n] = cs ? *(const f32x4*)(cs + col0 + bj * HALF + n * 4) : (f32x4){1.f, 1.f, 1.f, 1.f};
; #pragma unroll
;         for (int ai = 0; ai < 2; ++ai)
; #pragma unroll
;             for (int m = 0; m < 4; ++m) { const int row = u.pm * BM + ai * HALF + wr * 64 + m * 16 + fr; const size_t off = off0 + (size_t)(ai * HALF + m * 16) * 2048; float s = 0.f;
; #pragma unroll
;                 for (int bj = 0; bj < 2; ++bj) { const u32x4 w0 = bw[ai][m][bj];
;                     const f32x4 v0 = (f32x4){bf_lo(w0.x), bf_hi(w0.x), bf_lo(w0.y), bf_hi(w0.y)} + acc[ai][bj][m][0] * cv[bj][0];
;                     const f32x4 v1 = (f32x4){bf_lo(w0.z), bf_hi(w0.z), bf_lo(w0.w), bf_hi(w0.w)} + acc[ai][bj][m][1] * cv[bj][1];
;                     if (out) { *(f32x4*)(out + off + bj * HALF) = v0; *(f32x4*)(out + off + bj * HALF + 4) = v1; }
.LBB0_789:
	s_lshl_b32 s2, s50, 8
	v_mov_b32_e32 v79, v210
	v_mov_b32_e32 v213, v1
	s_or_b32 s2, s2, s43
	s_nop 0
	v_lshl_add_u32 v78, v213, 3, s2
	s_lshl_b32 s2, s80, 8
	s_add_i32 s2, s2, s42
	v_add_u32_e32 v202, s2, v79
	v_ashrrev_i32_e32 v203, 31, v202
	v_lshlrev_b64 v[80:81], 11, v[202:203]
	v_ashrrev_i32_e32 v79, 31, v78
	v_lshl_add_u64 v[206:207], v[80:81], 0, v[78:79]
	v_lshl_add_u64 v[204:205], v[206:207], 1, s[28:29]
	v_add_co_u32_e32 v78, vcc, s24, v204
	global_load_dwordx4 v[214:217], v[204:205], off
	global_load_dwordx4 v[186:189], v[204:205], off offset:256
	v_addc_co_u32_e32 v79, vcc, 0, v205, vcc
	global_load_dwordx4 v[182:185], v[78:79], off
	global_load_dwordx4 v[178:181], v[78:79], off offset:256
	v_add_co_u32_e32 v78, vcc, s19, v204
	s_nop 0
	s_nop 0
	v_addc_co_u32_e32 v79, vcc, 0, v205, vcc
	global_load_dwordx4 v[174:177], v[78:79], off
	global_load_dwordx4 v[170:173], v[78:79], off offset:256
	v_add_co_u32_e32 v78, vcc, s25, v204
	s_nop 0
	s_nop 0
	v_addc_co_u32_e32 v79, vcc, 0, v205, vcc
	global_load_dwordx4 v[166:169], v[78:79], off
	global_load_dwordx4 v[162:165], v[78:79], off offset:256
	v_add_co_u32_e32 v78, vcc, s1, v204
	s_nop 0
	s_nop 0
	v_addc_co_u32_e32 v79, vcc, 0, v205, vcc
	global_load_dwordx4 v[150:153], v[78:79], off
	global_load_dwordx4 v[146:149], v[78:79], off offset:256
	v_add_co_u32_e32 v78, vcc, s0, v204
	s_nop 0
	s_nop 0
	v_addc_co_u32_e32 v79, vcc, 0, v205, vcc
	global_load_dwordx4 v[134:137], v[78:79], off
	global_load_dwordx4 v[122:125], v[78:79], off offset:256
	v_add_co_u32_e32 v78, vcc, s64, v204
	s_nop 0
	s_nop 0
	v_addc_co_u32_e32 v79, vcc, 0, v205, vcc
	global_load_dwordx4 v[110:113], v[78:79], off
	global_load_dwordx4 v[102:105], v[78:79], off offset:256
	v_add_co_u32_e32 v78, vcc, s65, v204
	s_nop 0
	s_nop 0
	v_addc_co_u32_e32 v79, vcc, 0, v205, vcc
	global_load_dwordx4 v[86:89], v[78:79], off
	s_nop 0
	global_load_dwordx4 v[78:81], v[78:79], off offset:256
	s_waitcnt vmcnt(12)
	v_lshlrev_b32_e32 v208, 16, v214
	v_and_b32_e32 v209, 0xffff0000, v214
	v_lshlrev_b32_e32 v214, 16, v215
	v_and_b32_e32 v215, 0xffff0000, v215
	v_pk_add_f32 v[158:159], v[158:159], v[208:209]
	v_lshlrev_b32_e32 v208, 16, v216
	v_and_b32_e32 v209, 0xffff0000, v216
	v_pk_add_f32 v[160:161], v[160:161], v[214:215]
	v_lshlrev_b32_e32 v214, 16, v217
	v_and_b32_e32 v215, 0xffff0000, v217
	v_pk_add_f32 v[154:155], v[154:155], v[208:209]
	v_cndmask_b32_e64 v208, 0, 1, s[92:93]
	v_pk_add_f32 v[156:157], v[156:157], v[214:215]
	v_cmp_ne_u32_e64 s[4:5], 1, v208
	s_andn2_b64 vcc, exec, s[92:93]
	v_lshl_add_u64 v[208:209], v[206:207], 2, s[14:15]
	s_cbranch_vccnz .LBB0_791
	global_store_dwordx4 v[208:209], v[158:161], off
	global_store_dwordx4 v[208:209], v[154:157], off offset:16
